# v20
# speedup vs baseline: 1.0123x; 1.0123x over previous
; __device__ __forceinline__ void convert_phase(const Params& p, char* shm) {
;     ...
;     float4* z4 = (float4*)(p.ws + OFF_ST1);
;     int n4 = M_TOK * 2 * 2 / 4;
;     for (int i = blockIdx.x * 512 + threadIdx.x; i < n4; i += gridDim.x * 512) z4[i] = make_float4(0.f, 0.f, 0.f, 0.f);
.LBB0_554:
	s_cmp_lt_u32 s96, 0x100
	s_cbranch_scc0 .Lp6_nozero
	s_add_u32 s100, s90, 0x1da20000
	s_addc_u32 s101, s91, 0
	s_lshl_b32 s98, s96, 9
	v_lshlrev_b32_e32 v0, 4, v174
	v_add_u32_e32 v0, s98, v0
	v_mov_b32_e32 v4, 0
	v_mov_b32_e32 v5, 0
	v_mov_b32_e32 v6, 0
	v_mov_b32_e32 v7, 0
	v_cmp_gt_u32_e32 vcc, 32, v174
	s_and_saveexec_b64 s[98:99], vcc
	global_store_dwordx4 v0, v[4:7], s[100:101]
	s_or_b64 exec, exec, s[98:99]

; __device__ __forceinline__ float bf_lo(u32 v) { return __uint_as_float(v << 16); }
; __device__ __forceinline__ float bf_hi(u32 v) { return __uint_as_float(v & 0xFFFF0000u); }
; template <int EPI>
; __device__ __forceinline__ void gemm_phase(const u16* __restrict__ A, const u16* __restrict__ Bt, const int K,
;                                            const int nN, char* shm, const EpiArgs& ea) {
;     ...
;               float mu = 0.f, rstd = 1.f;
;               if (EPI != EPI_FFN1) row_stats(ea.st_in, row, mu, rstd);
;               float rs = 0.f, rq = 0.f;
; #pragma unroll
;               for (int bj = 0; bj < 2; ++bj) {
;                 uint2 pk[2];
; #pragma unroll
;                 for (int n = 0; n < 2; ++n) {
;                   const int col = cb + bj * 128 + n * 16;
;                   f32x4 c = acc[ai][bj][m][n];
;                   float h[4];
;                   if (EPI == EPI_FFN1) {
;                     float4 rv = *(const float4*)(ea.res + (size_t)row * DM + col);
;                     h[0] = rv.x; h[1] = rv.y; h[2] = rv.z; h[3] = rv.w;
;                   } else {
;                     uint2 yv = *(const uint2*)((const char*)ea.yb + tl_off(row, col, DM >> 6));
;                     float4 gv = *(const float4*)(ea.lng + col);
;                     float4 bv = *(const float4*)(ea.lnb + col);
;                     h[0] = (bf_lo(yv.x) - mu) * rstd * gv.x + bv.x; h[1] = (bf_hi(yv.x) - mu) * rstd * gv.y + bv.y;
;                     h[2] = (bf_lo(yv.y) - mu) * rstd * gv.z + bv.z; h[3] = (bf_hi(yv.y) - mu) * rstd * gv.w + bv.w;
;                   }
;                   float y[4];
;                   if (EPI == EPI_OUT) {
;                     float4 bo = *(const float4*)(ea.bias + col);
;                     y[0] = ALPHA * h[0] + c[0] + bo.x; y[1] = ALPHA * h[1] + c[1] + bo.y;
;                     y[2] = ALPHA * h[2] + c[2] + bo.z; y[3] = ALPHA * h[3] + c[3] + bo.w;
;                   } else {
; #pragma unroll
;                     for (int j = 0; j < 4; ++j) y[j] = ALPHA * h[j] + 0.5f * c[j];
;                   }
;                   if (EPI == EPI_FFN2) {
;                     *(float4*)(ea.outf + (size_t)row * DM + col) = make_float4(y[0], y[1], y[2], y[3]);
.LBB0_625:
	s_cmp_eq_u32 s94, 0x100
	s_cbranch_scc1 .Lp7_fused
	s_lshr_b32 s98, s33, 7
	s_mul_i32 s98, s98, 0x84000
	s_lshr_b32 s99, s47, 6
	s_lshl_b32 s99, s99, 14
	s_add_i32 s98, s98, s99
	v_add_u32_e32 v170, s33, v139
	v_add_u32_e32 v171, s47, v140
	v_lshlrev_b32_e32 v172, 3, v170
	v_lshlrev_b32_e32 v173, 2, v171
	global_load_dwordx2 v[150:151], v172, s[8:9]
	global_load_dwordx2 v[152:153], v172, s[8:9] offset:128
	global_load_dwordx2 v[154:155], v172, s[8:9] offset:256
	global_load_dwordx2 v[156:157], v172, s[8:9] offset:384
	global_load_dwordx2 v[158:159], v172, s[8:9] offset:1024
	global_load_dwordx2 v[160:161], v172, s[8:9] offset:1152
	global_load_dwordx2 v[162:163], v172, s[8:9] offset:1280
	global_load_dwordx2 v[164:165], v172, s[8:9] offset:1408
	global_load_dwordx4 v[176:179], v173, s[22:23]
	global_load_dwordx4 v[192:195], v173, s[76:77]
	global_load_dwordx4 v[180:183], v173, s[22:23] offset:64
	global_load_dwordx4 v[196:199], v173, s[76:77] offset:64
	global_load_dwordx4 v[184:187], v173, s[22:23] offset:512
	global_load_dwordx4 v[200:203], v173, s[76:77] offset:512
	global_load_dwordx4 v[188:191], v173, s[22:23] offset:576
	global_load_dwordx4 v[204:207], v173, s[76:77] offset:576
	v_and_b32_e32 v132, 15, v174
	v_lshlrev_b32_e32 v130, 6, v132
	v_and_b32_e32 v132, 48, v174
	v_lshrrev_b32_e32 v132, 1, v132
	v_or_b32_e32 v130, v130, v132
	v_and_b32_e32 v132, 64, v174
	v_lshl_or_b32 v130, v132, 4, v130
	v_and_b32_e32 v132, 0x80, v174
	v_lshl_or_b32 v130, v132, 7, v130
	v_and_b32_e32 v132, 0x100, v174
	v_lshl_or_b32 v130, v132, 5, v130
	v_add_u32_e32 v130, s98, v130
	v_and_b32_e32 v175, 8, v174
	v_lshlrev_b32_e32 v175, 2, v175
	v_sub_u32_e32 v131, v130, v175
	v_add_u32_e32 v131, 32, v131
	v_add_u32_e32 v130, v130, v175
	v_lshl_add_u32 v128, v170, 13, v173
	global_load_dwordx2 v[208:209], v130, s[10:11]
	global_load_dwordx2 v[210:211], v131, s[10:11]
	v_add_u32_e32 v132, 0x8000, v130
	global_load_dwordx2 v[212:213], v132, s[10:11]
	v_add_u32_e32 v149, 0x8000, v131
	global_load_dwordx2 v[214:215], v149, s[10:11]
	v_add_u32_e32 v132, 0x800, v130
	global_load_dwordx2 v[216:217], v132, s[10:11]
	v_add_u32_e32 v149, 0x800, v131
	global_load_dwordx2 v[218:219], v149, s[10:11]
	v_add_u32_e32 v132, 0x8800, v130
	global_load_dwordx2 v[220:221], v132, s[10:11]
	v_add_u32_e32 v149, 0x8800, v131
	global_load_dwordx2 v[222:223], v149, s[10:11]
	v_add_u32_e32 v132, 0x1000, v130
	global_load_dwordx2 v[224:225], v132, s[10:11]
	v_add_u32_e32 v149, 0x1000, v131
	global_load_dwordx2 v[226:227], v149, s[10:11]
	v_add_u32_e32 v132, 0x9000, v130
	global_load_dwordx2 v[228:229], v132, s[10:11]
	v_add_u32_e32 v149, 0x9000, v131
	global_load_dwordx2 v[230:231], v149, s[10:11]
	v_add_u32_e32 v132, 0x1800, v130
	global_load_dwordx2 v[232:233], v132, s[10:11]
	v_add_u32_e32 v149, 0x1800, v131
	global_load_dwordx2 v[234:235], v149, s[10:11]
	v_add_u32_e32 v132, 0x9800, v130
	global_load_dwordx2 v[236:237], v132, s[10:11]
	v_add_u32_e32 v149, 0x9800, v131
	global_load_dwordx2 v[238:239], v149, s[10:11]
	s_waitcnt vmcnt(31)
	v_pk_mul_f32 v[150:151], v[150:151], s[16:17] op_sel_hi:[1,0]
	v_mov_b32_e32 v133, v128
	v_fma_f32 v166, -v150, v150, v151
	v_max_f32_e32 v166, 0, v166
	v_add_f32_e32 v166, 0x3727c5ac, v166
	v_rsq_f32_e32 v166, v166
	s_nop 0
	s_waitcnt vmcnt(16)
	s_waitcnt vmcnt(15)
	v_lshlrev_b32_e32 v134, 16, v208
	v_and_b32_e32 v135, 0xffff0000, v208
	v_lshlrev_b32_e32 v136, 16, v209
	v_and_b32_e32 v137, 0xffff0000, v209
	v_pk_add_f32 v[134:135], v[134:135], v[150:151] op_sel_hi:[1,0] neg_lo:[0,1] neg_hi:[0,1]
	v_pk_add_f32 v[136:137], v[136:137], v[150:151] op_sel_hi:[1,0] neg_lo:[0,1] neg_hi:[0,1]
	v_pk_mul_f32 v[134:135], v[134:135], v[166:167] op_sel_hi:[1,0]
	v_pk_mul_f32 v[136:137], v[136:137], v[166:167] op_sel_hi:[1,0]
	v_pk_fma_f32 v[134:135], v[176:177], v[134:135], v[192:193]
	v_pk_fma_f32 v[136:137], v[178:179], v[136:137], v[194:195]
	v_pk_mul_f32 v[134:135], v[134:135], s[18:19] op_sel_hi:[1,0]
	v_pk_mul_f32 v[136:137], v[136:137], s[18:19] op_sel_hi:[1,0]
	v_pk_fma_f32 v[124:125], v[124:125], 0.5, v[134:135] op_sel_hi:[1,0,1]
	v_pk_fma_f32 v[126:127], v[126:127], 0.5, v[136:137] op_sel_hi:[1,0,1]
	global_store_dwordx4 v133, v[124:127], s[88:89]
	s_waitcnt vmcnt(15)
	v_lshlrev_b32_e32 v240, 16, v210
	v_and_b32_e32 v241, 0xffff0000, v210
	v_lshlrev_b32_e32 v242, 16, v211
	v_and_b32_e32 v243, 0xffff0000, v211
	v_pk_add_f32 v[240:241], v[240:241], v[150:151] op_sel_hi:[1,0] neg_lo:[0,1] neg_hi:[0,1]
	v_pk_add_f32 v[242:243], v[242:243], v[150:151] op_sel_hi:[1,0] neg_lo:[0,1] neg_hi:[0,1]
	v_pk_mul_f32 v[240:241], v[240:241], v[166:167] op_sel_hi:[1,0]
	v_pk_mul_f32 v[242:243], v[242:243], v[166:167] op_sel_hi:[1,0]
	v_pk_fma_f32 v[240:241], v[180:181], v[240:241], v[196:197]
	v_pk_fma_f32 v[242:243], v[182:183], v[242:243], v[198:199]
	v_pk_mul_f32 v[240:241], v[240:241], s[18:19] op_sel_hi:[1,0]
	v_pk_mul_f32 v[242:243], v[242:243], s[18:19] op_sel_hi:[1,0]
	v_pk_fma_f32 v[120:121], v[120:121], 0.5, v[240:241] op_sel_hi:[1,0,1]
	v_pk_fma_f32 v[122:123], v[122:123], 0.5, v[242:243] op_sel_hi:[1,0,1]
	global_store_dwordx4 v133, v[120:123], s[88:89] offset:64
	s_waitcnt vmcnt(15)
	v_lshlrev_b32_e32 v134, 16, v212
	v_and_b32_e32 v135, 0xffff0000, v212
	v_lshlrev_b32_e32 v136, 16, v213
	v_and_b32_e32 v137, 0xffff0000, v213
	v_pk_add_f32 v[134:135], v[134:135], v[150:151] op_sel_hi:[1,0] neg_lo:[0,1] neg_hi:[0,1]
	v_pk_add_f32 v[136:137], v[136:137], v[150:151] op_sel_hi:[1,0] neg_lo:[0,1] neg_hi:[0,1]
	v_pk_mul_f32 v[134:135], v[134:135], v[166:167] op_sel_hi:[1,0]
	v_pk_mul_f32 v[136:137], v[136:137], v[166:167] op_sel_hi:[1,0]
	v_pk_fma_f32 v[134:135], v[184:185], v[134:135], v[200:201]
	v_pk_fma_f32 v[136:137], v[186:187], v[136:137], v[202:203]
	v_pk_mul_f32 v[134:135], v[134:135], s[18:19] op_sel_hi:[1,0]
	v_pk_mul_f32 v[136:137], v[136:137], s[18:19] op_sel_hi:[1,0]
	v_pk_fma_f32 v[116:117], v[116:117], 0.5, v[134:135] op_sel_hi:[1,0,1]
	v_pk_fma_f32 v[118:119], v[118:119], 0.5, v[136:137] op_sel_hi:[1,0,1]
	global_store_dwordx4 v133, v[116:119], s[88:89] offset:512
	s_waitcnt vmcnt(15)
; __device__ __forceinline__ float bf_lo(u32 v) { return __uint_as_float(v << 16); }
; __device__ __forceinline__ void row_stats(const float* st, int row, float& mu, float& rstd) {
;   float2 v = *(const float2*)(st + (size_t)row * 2);
;   mu = v.x * (1.0f / DM);
;   float var = fmaxf(v.y * (1.0f / DM) - mu * mu, 0.f);
;   rstd = rsqrtf(var + LN_EPS);
; }
; template <int EPI>
; __device__ __forceinline__ void gemm_phase(const u16* __restrict__ A, const u16* __restrict__ Bt, const int K,
;                                            const int nN, char* shm, const EpiArgs& ea) {
;     ...
;               float mu = 0.f, rstd = 1.f;
;               if (EPI != EPI_FFN1) row_stats(ea.st_in, row, mu, rstd);
;               float rs = 0.f, rq = 0.f;
; #pragma unroll
;               for (int bj = 0; bj < 2; ++bj) {
;                 uint2 pk[2];
; #pragma unroll
;                 for (int n = 0; n < 2; ++n) {
;                   const int col = cb + bj * 128 + n * 16;
;                   f32x4 c = acc[ai][bj][m][n];
;                   float h[4];
;                   if (EPI == EPI_FFN1) {
;                     float4 rv = *(const float4*)(ea.res + (size_t)row * DM + col);
;                     h[0] = rv.x; h[1] = rv.y; h[2] = rv.z; h[3] = rv.w;
;                   } else {
;                     uint2 yv = *(const uint2*)((const char*)ea.yb + tl_off(row, col, DM >> 6));
;                     float4 gv = *(const float4*)(ea.lng + col);
;                     float4 bv = *(const float4*)(ea.lnb + col);
;                     h[0] = (bf_lo(yv.x) - mu) * rstd * gv.x + bv.x; h[1] = (bf_hi(yv.x) - mu) * rstd * gv.y + bv.y;
;                     h[2] = (bf_lo(yv.y) - mu) * rstd * gv.z + bv.z; h[3] = (bf_hi(yv.y) - mu) * rstd * gv.w + bv.w;
;                   }
;                   float y[4];
;                   if (EPI == EPI_OUT) {
;                     float4 bo = *(const float4*)(ea.bias + col);
;                     y[0] = ALPHA * h[0] + c[0] + bo.x; y[1] = ALPHA * h[1] + c[1] + bo.y;
;                     y[2] = ALPHA * h[2] + c[2] + bo.z; y[3] = ALPHA * h[3] + c[3] + bo.w;
;                   } else {
; #pragma unroll
;                     for (int j = 0; j < 4; ++j) y[j] = ALPHA * h[j] + 0.5f * c[j];
;                   }
;                   if (EPI == EPI_FFN2) {
;                     *(float4*)(ea.outf + (size_t)row * DM + col) = make_float4(y[0], y[1], y[2], y[3]);
	v_lshlrev_b32_e32 v240, 16, v214
	v_and_b32_e32 v241, 0xffff0000, v214
	v_lshlrev_b32_e32 v242, 16, v215
	v_and_b32_e32 v243, 0xffff0000, v215
	v_pk_add_f32 v[240:241], v[240:241], v[150:151] op_sel_hi:[1,0] neg_lo:[0,1] neg_hi:[0,1]
	v_pk_add_f32 v[242:243], v[242:243], v[150:151] op_sel_hi:[1,0] neg_lo:[0,1] neg_hi:[0,1]
	v_pk_mul_f32 v[240:241], v[240:241], v[166:167] op_sel_hi:[1,0]
	v_pk_mul_f32 v[242:243], v[242:243], v[166:167] op_sel_hi:[1,0]
	v_pk_fma_f32 v[240:241], v[188:189], v[240:241], v[204:205]
	v_pk_fma_f32 v[242:243], v[190:191], v[242:243], v[206:207]
	v_pk_mul_f32 v[240:241], v[240:241], s[18:19] op_sel_hi:[1,0]
	v_pk_mul_f32 v[242:243], v[242:243], s[18:19] op_sel_hi:[1,0]
	v_pk_fma_f32 v[112:113], v[112:113], 0.5, v[240:241] op_sel_hi:[1,0,1]
	v_pk_fma_f32 v[114:115], v[114:115], 0.5, v[242:243] op_sel_hi:[1,0,1]
	global_store_dwordx4 v133, v[112:115], s[88:89] offset:576
	v_add_u32_e32 v132, 0x84000, v130
	global_load_dwordx2 v[208:209], v132, s[10:11]
	v_add_u32_e32 v149, 0x84000, v131
	global_load_dwordx2 v[210:211], v149, s[10:11]
	v_add_u32_e32 v132, 0x8c000, v130
	global_load_dwordx2 v[212:213], v132, s[10:11]
	v_add_u32_e32 v149, 0x8c000, v131
	global_load_dwordx2 v[214:215], v149, s[10:11]
	v_pk_mul_f32 v[152:153], v[152:153], s[16:17] op_sel_hi:[1,0]
	v_add_u32_e32 v133, 0x20000, v128
	v_fma_f32 v168, -v152, v152, v153
	v_max_f32_e32 v168, 0, v168
	v_add_f32_e32 v168, 0x3727c5ac, v168
	v_rsq_f32_e32 v168, v168
	s_nop 0
	s_waitcnt vmcnt(19)
	v_lshlrev_b32_e32 v134, 16, v216
	v_and_b32_e32 v135, 0xffff0000, v216
	v_lshlrev_b32_e32 v136, 16, v217
	v_and_b32_e32 v137, 0xffff0000, v217
	v_pk_add_f32 v[134:135], v[134:135], v[152:153] op_sel_hi:[1,0] neg_lo:[0,1] neg_hi:[0,1]
	v_pk_add_f32 v[136:137], v[136:137], v[152:153] op_sel_hi:[1,0] neg_lo:[0,1] neg_hi:[0,1]
	v_pk_mul_f32 v[134:135], v[134:135], v[168:169] op_sel_hi:[1,0]
	v_pk_mul_f32 v[136:137], v[136:137], v[168:169] op_sel_hi:[1,0]
	v_pk_fma_f32 v[134:135], v[176:177], v[134:135], v[192:193]
	v_pk_fma_f32 v[136:137], v[178:179], v[136:137], v[194:195]
	v_pk_mul_f32 v[134:135], v[134:135], s[18:19] op_sel_hi:[1,0]
	v_pk_mul_f32 v[136:137], v[136:137], s[18:19] op_sel_hi:[1,0]
	v_pk_fma_f32 v[108:109], v[108:109], 0.5, v[134:135] op_sel_hi:[1,0,1]
	v_pk_fma_f32 v[110:111], v[110:111], 0.5, v[136:137] op_sel_hi:[1,0,1]
	global_store_dwordx4 v133, v[108:111], s[88:89]
	s_waitcnt vmcnt(19)
	v_lshlrev_b32_e32 v240, 16, v218
	v_and_b32_e32 v241, 0xffff0000, v218
	v_lshlrev_b32_e32 v242, 16, v219
	v_and_b32_e32 v243, 0xffff0000, v219
	v_pk_add_f32 v[240:241], v[240:241], v[152:153] op_sel_hi:[1,0] neg_lo:[0,1] neg_hi:[0,1]
	v_pk_add_f32 v[242:243], v[242:243], v[152:153] op_sel_hi:[1,0] neg_lo:[0,1] neg_hi:[0,1]
	v_pk_mul_f32 v[240:241], v[240:241], v[168:169] op_sel_hi:[1,0]
	v_pk_mul_f32 v[242:243], v[242:243], v[168:169] op_sel_hi:[1,0]
	v_pk_fma_f32 v[240:241], v[180:181], v[240:241], v[196:197]
	v_pk_fma_f32 v[242:243], v[182:183], v[242:243], v[198:199]
	v_pk_mul_f32 v[240:241], v[240:241], s[18:19] op_sel_hi:[1,0]
	v_pk_mul_f32 v[242:243], v[242:243], s[18:19] op_sel_hi:[1,0]
	v_pk_fma_f32 v[104:105], v[104:105], 0.5, v[240:241] op_sel_hi:[1,0,1]
	v_pk_fma_f32 v[106:107], v[106:107], 0.5, v[242:243] op_sel_hi:[1,0,1]
	global_store_dwordx4 v133, v[104:107], s[88:89] offset:64
	s_waitcnt vmcnt(19)
	v_lshlrev_b32_e32 v134, 16, v220
	v_and_b32_e32 v135, 0xffff0000, v220
	v_lshlrev_b32_e32 v136, 16, v221
	v_and_b32_e32 v137, 0xffff0000, v221
	v_pk_add_f32 v[134:135], v[134:135], v[152:153] op_sel_hi:[1,0] neg_lo:[0,1] neg_hi:[0,1]
	v_pk_add_f32 v[136:137], v[136:137], v[152:153] op_sel_hi:[1,0] neg_lo:[0,1] neg_hi:[0,1]
	v_pk_mul_f32 v[134:135], v[134:135], v[168:169] op_sel_hi:[1,0]
	v_pk_mul_f32 v[136:137], v[136:137], v[168:169] op_sel_hi:[1,0]
	v_pk_fma_f32 v[134:135], v[184:185], v[134:135], v[200:201]
	v_pk_fma_f32 v[136:137], v[186:187], v[136:137], v[202:203]
	v_pk_mul_f32 v[134:135], v[134:135], s[18:19] op_sel_hi:[1,0]
	v_pk_mul_f32 v[136:137], v[136:137], s[18:19] op_sel_hi:[1,0]
	v_pk_fma_f32 v[100:101], v[100:101], 0.5, v[134:135] op_sel_hi:[1,0,1]
	v_pk_fma_f32 v[102:103], v[102:103], 0.5, v[136:137] op_sel_hi:[1,0,1]
	global_store_dwordx4 v133, v[100:103], s[88:89] offset:512
	s_waitcnt vmcnt(19)
	v_lshlrev_b32_e32 v240, 16, v222
	v_and_b32_e32 v241, 0xffff0000, v222
	v_lshlrev_b32_e32 v242, 16, v223
	v_and_b32_e32 v243, 0xffff0000, v223
	v_pk_add_f32 v[240:241], v[240:241], v[152:153] op_sel_hi:[1,0] neg_lo:[0,1] neg_hi:[0,1]
	v_pk_add_f32 v[242:243], v[242:243], v[152:153] op_sel_hi:[1,0] neg_lo:[0,1] neg_hi:[0,1]
	v_pk_mul_f32 v[240:241], v[240:241], v[168:169] op_sel_hi:[1,0]
	v_pk_mul_f32 v[242:243], v[242:243], v[168:169] op_sel_hi:[1,0]
	v_pk_fma_f32 v[240:241], v[188:189], v[240:241], v[204:205]
	v_pk_fma_f32 v[242:243], v[190:191], v[242:243], v[206:207]
	v_pk_mul_f32 v[240:241], v[240:241], s[18:19] op_sel_hi:[1,0]
	v_pk_mul_f32 v[242:243], v[242:243], s[18:19] op_sel_hi:[1,0]
	v_pk_fma_f32 v[96:97], v[96:97], 0.5, v[240:241] op_sel_hi:[1,0,1]
	v_pk_fma_f32 v[98:99], v[98:99], 0.5, v[242:243] op_sel_hi:[1,0,1]
	global_store_dwordx4 v133, v[96:99], s[88:89] offset:576
	v_add_u32_e32 v132, 0x84800, v130
	global_load_dwordx2 v[216:217], v132, s[10:11]
	v_add_u32_e32 v149, 0x84800, v131
	global_load_dwordx2 v[218:219], v149, s[10:11]
	v_add_u32_e32 v132, 0x8c800, v130
	global_load_dwordx2 v[220:221], v132, s[10:11]
	v_add_u32_e32 v149, 0x8c800, v131
	global_load_dwordx2 v[222:223], v149, s[10:11]
	v_pk_mul_f32 v[154:155], v[154:155], s[16:17] op_sel_hi:[1,0]
	v_add_u32_e32 v133, 0x40000, v128
	v_fma_f32 v166, -v154, v154, v155
	v_max_f32_e32 v166, 0, v166
	v_add_f32_e32 v166, 0x3727c5ac, v166
	v_rsq_f32_e32 v166, v166
	s_nop 0
	s_waitcnt vmcnt(23)
; __device__ __forceinline__ float bf_lo(u32 v) { return __uint_as_float(v << 16); }
; __device__ __forceinline__ void row_stats(const float* st, int row, float& mu, float& rstd) {
;   float2 v = *(const float2*)(st + (size_t)row * 2);
;   mu = v.x * (1.0f / DM);
;   float var = fmaxf(v.y * (1.0f / DM) - mu * mu, 0.f);
;   rstd = rsqrtf(var + LN_EPS);
; }
; template <int EPI>
; __device__ __forceinline__ void gemm_phase(const u16* __restrict__ A, const u16* __restrict__ Bt, const int K,
;                                            const int nN, char* shm, const EpiArgs& ea) {
;     ...
;               float mu = 0.f, rstd = 1.f;
;               if (EPI != EPI_FFN1) row_stats(ea.st_in, row, mu, rstd);
;               float rs = 0.f, rq = 0.f;
; #pragma unroll
;               for (int bj = 0; bj < 2; ++bj) {
;                 uint2 pk[2];
; #pragma unroll
;                 for (int n = 0; n < 2; ++n) {
;                   const int col = cb + bj * 128 + n * 16;
;                   f32x4 c = acc[ai][bj][m][n];
;                   float h[4];
;                   if (EPI == EPI_FFN1) {
;                     float4 rv = *(const float4*)(ea.res + (size_t)row * DM + col);
;                     h[0] = rv.x; h[1] = rv.y; h[2] = rv.z; h[3] = rv.w;
;                   } else {
;                     uint2 yv = *(const uint2*)((const char*)ea.yb + tl_off(row, col, DM >> 6));
;                     float4 gv = *(const float4*)(ea.lng + col);
;                     float4 bv = *(const float4*)(ea.lnb + col);
;                     h[0] = (bf_lo(yv.x) - mu) * rstd * gv.x + bv.x; h[1] = (bf_hi(yv.x) - mu) * rstd * gv.y + bv.y;
;                     h[2] = (bf_lo(yv.y) - mu) * rstd * gv.z + bv.z; h[3] = (bf_hi(yv.y) - mu) * rstd * gv.w + bv.w;
;                   }
;                   float y[4];
;                   if (EPI == EPI_OUT) {
;                     float4 bo = *(const float4*)(ea.bias + col);
;                     y[0] = ALPHA * h[0] + c[0] + bo.x; y[1] = ALPHA * h[1] + c[1] + bo.y;
;                     y[2] = ALPHA * h[2] + c[2] + bo.z; y[3] = ALPHA * h[3] + c[3] + bo.w;
;                   } else {
; #pragma unroll
;                     for (int j = 0; j < 4; ++j) y[j] = ALPHA * h[j] + 0.5f * c[j];
;                   }
;                   if (EPI == EPI_FFN2) {
;                     *(float4*)(ea.outf + (size_t)row * DM + col) = make_float4(y[0], y[1], y[2], y[3]);
	v_lshlrev_b32_e32 v134, 16, v224
	v_and_b32_e32 v135, 0xffff0000, v224
	v_lshlrev_b32_e32 v136, 16, v225
	v_and_b32_e32 v137, 0xffff0000, v225
	v_pk_add_f32 v[134:135], v[134:135], v[154:155] op_sel_hi:[1,0] neg_lo:[0,1] neg_hi:[0,1]
	v_pk_add_f32 v[136:137], v[136:137], v[154:155] op_sel_hi:[1,0] neg_lo:[0,1] neg_hi:[0,1]
	v_pk_mul_f32 v[134:135], v[134:135], v[166:167] op_sel_hi:[1,0]
	v_pk_mul_f32 v[136:137], v[136:137], v[166:167] op_sel_hi:[1,0]
	v_pk_fma_f32 v[134:135], v[176:177], v[134:135], v[192:193]
	v_pk_fma_f32 v[136:137], v[178:179], v[136:137], v[194:195]
	v_pk_mul_f32 v[134:135], v[134:135], s[18:19] op_sel_hi:[1,0]
	v_pk_mul_f32 v[136:137], v[136:137], s[18:19] op_sel_hi:[1,0]
	v_pk_fma_f32 v[92:93], v[92:93], 0.5, v[134:135] op_sel_hi:[1,0,1]
	v_pk_fma_f32 v[94:95], v[94:95], 0.5, v[136:137] op_sel_hi:[1,0,1]
	global_store_dwordx4 v133, v[92:95], s[88:89]
	s_waitcnt vmcnt(23)
	v_lshlrev_b32_e32 v240, 16, v226
	v_and_b32_e32 v241, 0xffff0000, v226
	v_lshlrev_b32_e32 v242, 16, v227
	v_and_b32_e32 v243, 0xffff0000, v227
	v_pk_add_f32 v[240:241], v[240:241], v[154:155] op_sel_hi:[1,0] neg_lo:[0,1] neg_hi:[0,1]
	v_pk_add_f32 v[242:243], v[242:243], v[154:155] op_sel_hi:[1,0] neg_lo:[0,1] neg_hi:[0,1]
	v_pk_mul_f32 v[240:241], v[240:241], v[166:167] op_sel_hi:[1,0]
	v_pk_mul_f32 v[242:243], v[242:243], v[166:167] op_sel_hi:[1,0]
	v_pk_fma_f32 v[240:241], v[180:181], v[240:241], v[196:197]
	v_pk_fma_f32 v[242:243], v[182:183], v[242:243], v[198:199]
	v_pk_mul_f32 v[240:241], v[240:241], s[18:19] op_sel_hi:[1,0]
	v_pk_mul_f32 v[242:243], v[242:243], s[18:19] op_sel_hi:[1,0]
	v_pk_fma_f32 v[88:89], v[88:89], 0.5, v[240:241] op_sel_hi:[1,0,1]
	v_pk_fma_f32 v[90:91], v[90:91], 0.5, v[242:243] op_sel_hi:[1,0,1]
	global_store_dwordx4 v133, v[88:91], s[88:89] offset:64
	s_waitcnt vmcnt(23)
	v_lshlrev_b32_e32 v134, 16, v228
	v_and_b32_e32 v135, 0xffff0000, v228
	v_lshlrev_b32_e32 v136, 16, v229
	v_and_b32_e32 v137, 0xffff0000, v229
	v_pk_add_f32 v[134:135], v[134:135], v[154:155] op_sel_hi:[1,0] neg_lo:[0,1] neg_hi:[0,1]
	v_pk_add_f32 v[136:137], v[136:137], v[154:155] op_sel_hi:[1,0] neg_lo:[0,1] neg_hi:[0,1]
	v_pk_mul_f32 v[134:135], v[134:135], v[166:167] op_sel_hi:[1,0]
	v_pk_mul_f32 v[136:137], v[136:137], v[166:167] op_sel_hi:[1,0]
	v_pk_fma_f32 v[134:135], v[184:185], v[134:135], v[200:201]
	v_pk_fma_f32 v[136:137], v[186:187], v[136:137], v[202:203]
	v_pk_mul_f32 v[134:135], v[134:135], s[18:19] op_sel_hi:[1,0]
	v_pk_mul_f32 v[136:137], v[136:137], s[18:19] op_sel_hi:[1,0]
	v_pk_fma_f32 v[84:85], v[84:85], 0.5, v[134:135] op_sel_hi:[1,0,1]
	v_pk_fma_f32 v[86:87], v[86:87], 0.5, v[136:137] op_sel_hi:[1,0,1]
	global_store_dwordx4 v133, v[84:87], s[88:89] offset:512
	s_waitcnt vmcnt(23)
	v_lshlrev_b32_e32 v240, 16, v230
	v_and_b32_e32 v241, 0xffff0000, v230
	v_lshlrev_b32_e32 v242, 16, v231
	v_and_b32_e32 v243, 0xffff0000, v231
	v_pk_add_f32 v[240:241], v[240:241], v[154:155] op_sel_hi:[1,0] neg_lo:[0,1] neg_hi:[0,1]
	v_pk_add_f32 v[242:243], v[242:243], v[154:155] op_sel_hi:[1,0] neg_lo:[0,1] neg_hi:[0,1]
	v_pk_mul_f32 v[240:241], v[240:241], v[166:167] op_sel_hi:[1,0]
	v_pk_mul_f32 v[242:243], v[242:243], v[166:167] op_sel_hi:[1,0]
	v_pk_fma_f32 v[240:241], v[188:189], v[240:241], v[204:205]
	v_pk_fma_f32 v[242:243], v[190:191], v[242:243], v[206:207]
	v_pk_mul_f32 v[240:241], v[240:241], s[18:19] op_sel_hi:[1,0]
	v_pk_mul_f32 v[242:243], v[242:243], s[18:19] op_sel_hi:[1,0]
	v_pk_fma_f32 v[80:81], v[80:81], 0.5, v[240:241] op_sel_hi:[1,0,1]
	v_pk_fma_f32 v[82:83], v[82:83], 0.5, v[242:243] op_sel_hi:[1,0,1]
	global_store_dwordx4 v133, v[80:83], s[88:89] offset:576
	v_add_u32_e32 v132, 0x85000, v130
	global_load_dwordx2 v[224:225], v132, s[10:11]
	v_add_u32_e32 v149, 0x85000, v131
	global_load_dwordx2 v[226:227], v149, s[10:11]
	v_add_u32_e32 v132, 0x8d000, v130
	global_load_dwordx2 v[228:229], v132, s[10:11]
	v_add_u32_e32 v149, 0x8d000, v131
	global_load_dwordx2 v[230:231], v149, s[10:11]
	v_pk_mul_f32 v[156:157], v[156:157], s[16:17] op_sel_hi:[1,0]
	v_add_u32_e32 v133, 0x60000, v128
	v_fma_f32 v168, -v156, v156, v157
	v_max_f32_e32 v168, 0, v168
	v_add_f32_e32 v168, 0x3727c5ac, v168
	v_rsq_f32_e32 v168, v168
	s_nop 0
	s_waitcnt vmcnt(27)
	v_lshlrev_b32_e32 v134, 16, v232
	v_and_b32_e32 v135, 0xffff0000, v232
	v_lshlrev_b32_e32 v136, 16, v233
	v_and_b32_e32 v137, 0xffff0000, v233
	v_pk_add_f32 v[134:135], v[134:135], v[156:157] op_sel_hi:[1,0] neg_lo:[0,1] neg_hi:[0,1]
	v_pk_add_f32 v[136:137], v[136:137], v[156:157] op_sel_hi:[1,0] neg_lo:[0,1] neg_hi:[0,1]
	v_pk_mul_f32 v[134:135], v[134:135], v[168:169] op_sel_hi:[1,0]
	v_pk_mul_f32 v[136:137], v[136:137], v[168:169] op_sel_hi:[1,0]
	v_pk_fma_f32 v[134:135], v[176:177], v[134:135], v[192:193]
	v_pk_fma_f32 v[136:137], v[178:179], v[136:137], v[194:195]
	v_pk_mul_f32 v[134:135], v[134:135], s[18:19] op_sel_hi:[1,0]
	v_pk_mul_f32 v[136:137], v[136:137], s[18:19] op_sel_hi:[1,0]
	v_pk_fma_f32 v[76:77], v[76:77], 0.5, v[134:135] op_sel_hi:[1,0,1]
	v_pk_fma_f32 v[78:79], v[78:79], 0.5, v[136:137] op_sel_hi:[1,0,1]
	global_store_dwordx4 v133, v[76:79], s[88:89]
	s_waitcnt vmcnt(27)
	v_lshlrev_b32_e32 v240, 16, v234
	v_and_b32_e32 v241, 0xffff0000, v234
	v_lshlrev_b32_e32 v242, 16, v235
	v_and_b32_e32 v243, 0xffff0000, v235
	v_pk_add_f32 v[240:241], v[240:241], v[156:157] op_sel_hi:[1,0] neg_lo:[0,1] neg_hi:[0,1]
	v_pk_add_f32 v[242:243], v[242:243], v[156:157] op_sel_hi:[1,0] neg_lo:[0,1] neg_hi:[0,1]
	v_pk_mul_f32 v[240:241], v[240:241], v[168:169] op_sel_hi:[1,0]
	v_pk_mul_f32 v[242:243], v[242:243], v[168:169] op_sel_hi:[1,0]
	v_pk_fma_f32 v[240:241], v[180:181], v[240:241], v[196:197]
	v_pk_fma_f32 v[242:243], v[182:183], v[242:243], v[198:199]
	v_pk_mul_f32 v[240:241], v[240:241], s[18:19] op_sel_hi:[1,0]
	v_pk_mul_f32 v[242:243], v[242:243], s[18:19] op_sel_hi:[1,0]
	v_pk_fma_f32 v[72:73], v[72:73], 0.5, v[240:241] op_sel_hi:[1,0,1]
	v_pk_fma_f32 v[74:75], v[74:75], 0.5, v[242:243] op_sel_hi:[1,0,1]
	global_store_dwordx4 v133, v[72:75], s[88:89] offset:64
	s_waitcnt vmcnt(27)
; __device__ __forceinline__ float bf_lo(u32 v) { return __uint_as_float(v << 16); }
; __device__ __forceinline__ void row_stats(const float* st, int row, float& mu, float& rstd) {
;   float2 v = *(const float2*)(st + (size_t)row * 2);
;   mu = v.x * (1.0f / DM);
;   float var = fmaxf(v.y * (1.0f / DM) - mu * mu, 0.f);
;   rstd = rsqrtf(var + LN_EPS);
; }
; template <int EPI>
; __device__ __forceinline__ void gemm_phase(const u16* __restrict__ A, const u16* __restrict__ Bt, const int K,
;                                            const int nN, char* shm, const EpiArgs& ea) {
;     ...
;               float mu = 0.f, rstd = 1.f;
;               if (EPI != EPI_FFN1) row_stats(ea.st_in, row, mu, rstd);
;               float rs = 0.f, rq = 0.f;
; #pragma unroll
;               for (int bj = 0; bj < 2; ++bj) {
;                 uint2 pk[2];
; #pragma unroll
;                 for (int n = 0; n < 2; ++n) {
;                   const int col = cb + bj * 128 + n * 16;
;                   f32x4 c = acc[ai][bj][m][n];
;                   float h[4];
;                   if (EPI == EPI_FFN1) {
;                     float4 rv = *(const float4*)(ea.res + (size_t)row * DM + col);
;                     h[0] = rv.x; h[1] = rv.y; h[2] = rv.z; h[3] = rv.w;
;                   } else {
;                     uint2 yv = *(const uint2*)((const char*)ea.yb + tl_off(row, col, DM >> 6));
;                     float4 gv = *(const float4*)(ea.lng + col);
;                     float4 bv = *(const float4*)(ea.lnb + col);
;                     h[0] = (bf_lo(yv.x) - mu) * rstd * gv.x + bv.x; h[1] = (bf_hi(yv.x) - mu) * rstd * gv.y + bv.y;
;                     h[2] = (bf_lo(yv.y) - mu) * rstd * gv.z + bv.z; h[3] = (bf_hi(yv.y) - mu) * rstd * gv.w + bv.w;
;                   }
;                   float y[4];
;                   if (EPI == EPI_OUT) {
;                     float4 bo = *(const float4*)(ea.bias + col);
;                     y[0] = ALPHA * h[0] + c[0] + bo.x; y[1] = ALPHA * h[1] + c[1] + bo.y;
;                     y[2] = ALPHA * h[2] + c[2] + bo.z; y[3] = ALPHA * h[3] + c[3] + bo.w;
;                   } else {
; #pragma unroll
;                     for (int j = 0; j < 4; ++j) y[j] = ALPHA * h[j] + 0.5f * c[j];
;                   }
;                   if (EPI == EPI_FFN2) {
;                     *(float4*)(ea.outf + (size_t)row * DM + col) = make_float4(y[0], y[1], y[2], y[3]);
	v_lshlrev_b32_e32 v134, 16, v236
	v_and_b32_e32 v135, 0xffff0000, v236
	v_lshlrev_b32_e32 v136, 16, v237
	v_and_b32_e32 v137, 0xffff0000, v237
	v_pk_add_f32 v[134:135], v[134:135], v[156:157] op_sel_hi:[1,0] neg_lo:[0,1] neg_hi:[0,1]
	v_pk_add_f32 v[136:137], v[136:137], v[156:157] op_sel_hi:[1,0] neg_lo:[0,1] neg_hi:[0,1]
	v_pk_mul_f32 v[134:135], v[134:135], v[168:169] op_sel_hi:[1,0]
	v_pk_mul_f32 v[136:137], v[136:137], v[168:169] op_sel_hi:[1,0]
	v_pk_fma_f32 v[134:135], v[184:185], v[134:135], v[200:201]
	v_pk_fma_f32 v[136:137], v[186:187], v[136:137], v[202:203]
	v_pk_mul_f32 v[134:135], v[134:135], s[18:19] op_sel_hi:[1,0]
	v_pk_mul_f32 v[136:137], v[136:137], s[18:19] op_sel_hi:[1,0]
	v_pk_fma_f32 v[68:69], v[68:69], 0.5, v[134:135] op_sel_hi:[1,0,1]
	v_pk_fma_f32 v[70:71], v[70:71], 0.5, v[136:137] op_sel_hi:[1,0,1]
	global_store_dwordx4 v133, v[68:71], s[88:89] offset:512
	s_waitcnt vmcnt(27)
	v_lshlrev_b32_e32 v240, 16, v238
	v_and_b32_e32 v241, 0xffff0000, v238
	v_lshlrev_b32_e32 v242, 16, v239
	v_and_b32_e32 v243, 0xffff0000, v239
	v_pk_add_f32 v[240:241], v[240:241], v[156:157] op_sel_hi:[1,0] neg_lo:[0,1] neg_hi:[0,1]
	v_pk_add_f32 v[242:243], v[242:243], v[156:157] op_sel_hi:[1,0] neg_lo:[0,1] neg_hi:[0,1]
	v_pk_mul_f32 v[240:241], v[240:241], v[168:169] op_sel_hi:[1,0]
	v_pk_mul_f32 v[242:243], v[242:243], v[168:169] op_sel_hi:[1,0]
	v_pk_fma_f32 v[240:241], v[188:189], v[240:241], v[204:205]
	v_pk_fma_f32 v[242:243], v[190:191], v[242:243], v[206:207]
	v_pk_mul_f32 v[240:241], v[240:241], s[18:19] op_sel_hi:[1,0]
	v_pk_mul_f32 v[242:243], v[242:243], s[18:19] op_sel_hi:[1,0]
	v_pk_fma_f32 v[64:65], v[64:65], 0.5, v[240:241] op_sel_hi:[1,0,1]
	v_pk_fma_f32 v[66:67], v[66:67], 0.5, v[242:243] op_sel_hi:[1,0,1]
	global_store_dwordx4 v133, v[64:67], s[88:89] offset:576
	v_add_u32_e32 v132, 0x85800, v130
	global_load_dwordx2 v[232:233], v132, s[10:11]
	v_add_u32_e32 v149, 0x85800, v131
	global_load_dwordx2 v[234:235], v149, s[10:11]
	v_add_u32_e32 v132, 0x8d800, v130
	global_load_dwordx2 v[236:237], v132, s[10:11]
	v_add_u32_e32 v149, 0x8d800, v131
	global_load_dwordx2 v[238:239], v149, s[10:11]
	v_pk_mul_f32 v[158:159], v[158:159], s[16:17] op_sel_hi:[1,0]
	v_add_u32_e32 v133, 0x100000, v128
	v_fma_f32 v166, -v158, v158, v159
	v_max_f32_e32 v166, 0, v166
	v_add_f32_e32 v166, 0x3727c5ac, v166
	v_rsq_f32_e32 v166, v166
	s_nop 0
	s_waitcnt vmcnt(27)
	v_lshlrev_b32_e32 v134, 16, v208
	v_and_b32_e32 v135, 0xffff0000, v208
	v_lshlrev_b32_e32 v136, 16, v209
	v_and_b32_e32 v137, 0xffff0000, v209
	v_pk_add_f32 v[134:135], v[134:135], v[158:159] op_sel_hi:[1,0] neg_lo:[0,1] neg_hi:[0,1]
	v_pk_add_f32 v[136:137], v[136:137], v[158:159] op_sel_hi:[1,0] neg_lo:[0,1] neg_hi:[0,1]
	v_pk_mul_f32 v[134:135], v[134:135], v[166:167] op_sel_hi:[1,0]
	v_pk_mul_f32 v[136:137], v[136:137], v[166:167] op_sel_hi:[1,0]
	v_pk_fma_f32 v[134:135], v[176:177], v[134:135], v[192:193]
	v_pk_fma_f32 v[136:137], v[178:179], v[136:137], v[194:195]
	v_pk_mul_f32 v[134:135], v[134:135], s[18:19] op_sel_hi:[1,0]
	v_pk_mul_f32 v[136:137], v[136:137], s[18:19] op_sel_hi:[1,0]
	v_pk_fma_f32 v[60:61], v[60:61], 0.5, v[134:135] op_sel_hi:[1,0,1]
	v_pk_fma_f32 v[62:63], v[62:63], 0.5, v[136:137] op_sel_hi:[1,0,1]
	global_store_dwordx4 v133, v[60:63], s[88:89]
	s_waitcnt vmcnt(27)
	v_lshlrev_b32_e32 v240, 16, v210
	v_and_b32_e32 v241, 0xffff0000, v210
	v_lshlrev_b32_e32 v242, 16, v211
	v_and_b32_e32 v243, 0xffff0000, v211
	v_pk_add_f32 v[240:241], v[240:241], v[158:159] op_sel_hi:[1,0] neg_lo:[0,1] neg_hi:[0,1]
	v_pk_add_f32 v[242:243], v[242:243], v[158:159] op_sel_hi:[1,0] neg_lo:[0,1] neg_hi:[0,1]
	v_pk_mul_f32 v[240:241], v[240:241], v[166:167] op_sel_hi:[1,0]
	v_pk_mul_f32 v[242:243], v[242:243], v[166:167] op_sel_hi:[1,0]
	v_pk_fma_f32 v[240:241], v[180:181], v[240:241], v[196:197]
	v_pk_fma_f32 v[242:243], v[182:183], v[242:243], v[198:199]
	v_pk_mul_f32 v[240:241], v[240:241], s[18:19] op_sel_hi:[1,0]
	v_pk_mul_f32 v[242:243], v[242:243], s[18:19] op_sel_hi:[1,0]
	v_pk_fma_f32 v[56:57], v[56:57], 0.5, v[240:241] op_sel_hi:[1,0,1]
	v_pk_fma_f32 v[58:59], v[58:59], 0.5, v[242:243] op_sel_hi:[1,0,1]
	global_store_dwordx4 v133, v[56:59], s[88:89] offset:64
	s_waitcnt vmcnt(27)
	v_lshlrev_b32_e32 v134, 16, v212
	v_and_b32_e32 v135, 0xffff0000, v212
	v_lshlrev_b32_e32 v136, 16, v213
	v_and_b32_e32 v137, 0xffff0000, v213
	v_pk_add_f32 v[134:135], v[134:135], v[158:159] op_sel_hi:[1,0] neg_lo:[0,1] neg_hi:[0,1]
	v_pk_add_f32 v[136:137], v[136:137], v[158:159] op_sel_hi:[1,0] neg_lo:[0,1] neg_hi:[0,1]
	v_pk_mul_f32 v[134:135], v[134:135], v[166:167] op_sel_hi:[1,0]
	v_pk_mul_f32 v[136:137], v[136:137], v[166:167] op_sel_hi:[1,0]
	v_pk_fma_f32 v[134:135], v[184:185], v[134:135], v[200:201]
	v_pk_fma_f32 v[136:137], v[186:187], v[136:137], v[202:203]
	v_pk_mul_f32 v[134:135], v[134:135], s[18:19] op_sel_hi:[1,0]
	v_pk_mul_f32 v[136:137], v[136:137], s[18:19] op_sel_hi:[1,0]
	v_pk_fma_f32 v[52:53], v[52:53], 0.5, v[134:135] op_sel_hi:[1,0,1]
	v_pk_fma_f32 v[54:55], v[54:55], 0.5, v[136:137] op_sel_hi:[1,0,1]
	global_store_dwordx4 v133, v[52:55], s[88:89] offset:512
	s_waitcnt vmcnt(27)
; __device__ __forceinline__ float bf_lo(u32 v) { return __uint_as_float(v << 16); }
; __device__ __forceinline__ void row_stats(const float* st, int row, float& mu, float& rstd) {
;   float2 v = *(const float2*)(st + (size_t)row * 2);
;   mu = v.x * (1.0f / DM);
;   float var = fmaxf(v.y * (1.0f / DM) - mu * mu, 0.f);
;   rstd = rsqrtf(var + LN_EPS);
; }
; template <int EPI>
; __device__ __forceinline__ void gemm_phase(const u16* __restrict__ A, const u16* __restrict__ Bt, const int K,
;                                            const int nN, char* shm, const EpiArgs& ea) {
;     ...
;               float mu = 0.f, rstd = 1.f;
;               if (EPI != EPI_FFN1) row_stats(ea.st_in, row, mu, rstd);
;               float rs = 0.f, rq = 0.f;
; #pragma unroll
;               for (int bj = 0; bj < 2; ++bj) {
;                 uint2 pk[2];
; #pragma unroll
;                 for (int n = 0; n < 2; ++n) {
;                   const int col = cb + bj * 128 + n * 16;
;                   f32x4 c = acc[ai][bj][m][n];
;                   float h[4];
;                   if (EPI == EPI_FFN1) {
;                     float4 rv = *(const float4*)(ea.res + (size_t)row * DM + col);
;                     h[0] = rv.x; h[1] = rv.y; h[2] = rv.z; h[3] = rv.w;
;                   } else {
;                     uint2 yv = *(const uint2*)((const char*)ea.yb + tl_off(row, col, DM >> 6));
;                     float4 gv = *(const float4*)(ea.lng + col);
;                     float4 bv = *(const float4*)(ea.lnb + col);
;                     h[0] = (bf_lo(yv.x) - mu) * rstd * gv.x + bv.x; h[1] = (bf_hi(yv.x) - mu) * rstd * gv.y + bv.y;
;                     h[2] = (bf_lo(yv.y) - mu) * rstd * gv.z + bv.z; h[3] = (bf_hi(yv.y) - mu) * rstd * gv.w + bv.w;
;                   }
;                   float y[4];
;                   if (EPI == EPI_OUT) {
;                     float4 bo = *(const float4*)(ea.bias + col);
;                     y[0] = ALPHA * h[0] + c[0] + bo.x; y[1] = ALPHA * h[1] + c[1] + bo.y;
;                     y[2] = ALPHA * h[2] + c[2] + bo.z; y[3] = ALPHA * h[3] + c[3] + bo.w;
;                   } else {
; #pragma unroll
;                     for (int j = 0; j < 4; ++j) y[j] = ALPHA * h[j] + 0.5f * c[j];
;                   }
;                   if (EPI == EPI_FFN2) {
;                     *(float4*)(ea.outf + (size_t)row * DM + col) = make_float4(y[0], y[1], y[2], y[3]);
	v_lshlrev_b32_e32 v240, 16, v214
	v_and_b32_e32 v241, 0xffff0000, v214
	v_lshlrev_b32_e32 v242, 16, v215
	v_and_b32_e32 v243, 0xffff0000, v215
	v_pk_add_f32 v[240:241], v[240:241], v[158:159] op_sel_hi:[1,0] neg_lo:[0,1] neg_hi:[0,1]
	v_pk_add_f32 v[242:243], v[242:243], v[158:159] op_sel_hi:[1,0] neg_lo:[0,1] neg_hi:[0,1]
	v_pk_mul_f32 v[240:241], v[240:241], v[166:167] op_sel_hi:[1,0]
	v_pk_mul_f32 v[242:243], v[242:243], v[166:167] op_sel_hi:[1,0]
	v_pk_fma_f32 v[240:241], v[188:189], v[240:241], v[204:205]
	v_pk_fma_f32 v[242:243], v[190:191], v[242:243], v[206:207]
	v_pk_mul_f32 v[240:241], v[240:241], s[18:19] op_sel_hi:[1,0]
	v_pk_mul_f32 v[242:243], v[242:243], s[18:19] op_sel_hi:[1,0]
	v_pk_fma_f32 v[48:49], v[48:49], 0.5, v[240:241] op_sel_hi:[1,0,1]
	v_pk_fma_f32 v[50:51], v[50:51], 0.5, v[242:243] op_sel_hi:[1,0,1]
	global_store_dwordx4 v133, v[48:51], s[88:89] offset:576
	v_pk_mul_f32 v[160:161], v[160:161], s[16:17] op_sel_hi:[1,0]
	v_add_u32_e32 v133, 0x120000, v128
	v_fma_f32 v168, -v160, v160, v161
	v_max_f32_e32 v168, 0, v168
	v_add_f32_e32 v168, 0x3727c5ac, v168
	v_rsq_f32_e32 v168, v168
	s_nop 0
	s_waitcnt vmcnt(23)
	v_lshlrev_b32_e32 v134, 16, v216
	v_and_b32_e32 v135, 0xffff0000, v216
	v_lshlrev_b32_e32 v136, 16, v217
	v_and_b32_e32 v137, 0xffff0000, v217
	v_pk_add_f32 v[134:135], v[134:135], v[160:161] op_sel_hi:[1,0] neg_lo:[0,1] neg_hi:[0,1]
	v_pk_add_f32 v[136:137], v[136:137], v[160:161] op_sel_hi:[1,0] neg_lo:[0,1] neg_hi:[0,1]
	v_pk_mul_f32 v[134:135], v[134:135], v[168:169] op_sel_hi:[1,0]
	v_pk_mul_f32 v[136:137], v[136:137], v[168:169] op_sel_hi:[1,0]
	v_pk_fma_f32 v[134:135], v[176:177], v[134:135], v[192:193]
	v_pk_fma_f32 v[136:137], v[178:179], v[136:137], v[194:195]
	v_pk_mul_f32 v[134:135], v[134:135], s[18:19] op_sel_hi:[1,0]
	v_pk_mul_f32 v[136:137], v[136:137], s[18:19] op_sel_hi:[1,0]
	v_pk_fma_f32 v[44:45], v[44:45], 0.5, v[134:135] op_sel_hi:[1,0,1]
	v_pk_fma_f32 v[46:47], v[46:47], 0.5, v[136:137] op_sel_hi:[1,0,1]
	global_store_dwordx4 v133, v[44:47], s[88:89]
	s_waitcnt vmcnt(23)
	v_lshlrev_b32_e32 v240, 16, v218
	v_and_b32_e32 v241, 0xffff0000, v218
	v_lshlrev_b32_e32 v242, 16, v219
	v_and_b32_e32 v243, 0xffff0000, v219
	v_pk_add_f32 v[240:241], v[240:241], v[160:161] op_sel_hi:[1,0] neg_lo:[0,1] neg_hi:[0,1]
	v_pk_add_f32 v[242:243], v[242:243], v[160:161] op_sel_hi:[1,0] neg_lo:[0,1] neg_hi:[0,1]
	v_pk_mul_f32 v[240:241], v[240:241], v[168:169] op_sel_hi:[1,0]
	v_pk_mul_f32 v[242:243], v[242:243], v[168:169] op_sel_hi:[1,0]
	v_pk_fma_f32 v[240:241], v[180:181], v[240:241], v[196:197]
	v_pk_fma_f32 v[242:243], v[182:183], v[242:243], v[198:199]
	v_pk_mul_f32 v[240:241], v[240:241], s[18:19] op_sel_hi:[1,0]
	v_pk_mul_f32 v[242:243], v[242:243], s[18:19] op_sel_hi:[1,0]
	v_pk_fma_f32 v[40:41], v[40:41], 0.5, v[240:241] op_sel_hi:[1,0,1]
	v_pk_fma_f32 v[42:43], v[42:43], 0.5, v[242:243] op_sel_hi:[1,0,1]
	global_store_dwordx4 v133, v[40:43], s[88:89] offset:64
	s_waitcnt vmcnt(23)
	v_lshlrev_b32_e32 v134, 16, v220
	v_and_b32_e32 v135, 0xffff0000, v220
	v_lshlrev_b32_e32 v136, 16, v221
	v_and_b32_e32 v137, 0xffff0000, v221
	v_pk_add_f32 v[134:135], v[134:135], v[160:161] op_sel_hi:[1,0] neg_lo:[0,1] neg_hi:[0,1]
	v_pk_add_f32 v[136:137], v[136:137], v[160:161] op_sel_hi:[1,0] neg_lo:[0,1] neg_hi:[0,1]
	v_pk_mul_f32 v[134:135], v[134:135], v[168:169] op_sel_hi:[1,0]
	v_pk_mul_f32 v[136:137], v[136:137], v[168:169] op_sel_hi:[1,0]
	v_pk_fma_f32 v[134:135], v[184:185], v[134:135], v[200:201]
	v_pk_fma_f32 v[136:137], v[186:187], v[136:137], v[202:203]
	v_pk_mul_f32 v[134:135], v[134:135], s[18:19] op_sel_hi:[1,0]
	v_pk_mul_f32 v[136:137], v[136:137], s[18:19] op_sel_hi:[1,0]
	v_pk_fma_f32 v[36:37], v[36:37], 0.5, v[134:135] op_sel_hi:[1,0,1]
	v_pk_fma_f32 v[38:39], v[38:39], 0.5, v[136:137] op_sel_hi:[1,0,1]
	global_store_dwordx4 v133, v[36:39], s[88:89] offset:512
	s_waitcnt vmcnt(23)
	v_lshlrev_b32_e32 v240, 16, v222
	v_and_b32_e32 v241, 0xffff0000, v222
	v_lshlrev_b32_e32 v242, 16, v223
	v_and_b32_e32 v243, 0xffff0000, v223
	v_pk_add_f32 v[240:241], v[240:241], v[160:161] op_sel_hi:[1,0] neg_lo:[0,1] neg_hi:[0,1]
	v_pk_add_f32 v[242:243], v[242:243], v[160:161] op_sel_hi:[1,0] neg_lo:[0,1] neg_hi:[0,1]
	v_pk_mul_f32 v[240:241], v[240:241], v[168:169] op_sel_hi:[1,0]
	v_pk_mul_f32 v[242:243], v[242:243], v[168:169] op_sel_hi:[1,0]
	v_pk_fma_f32 v[240:241], v[188:189], v[240:241], v[204:205]
	v_pk_fma_f32 v[242:243], v[190:191], v[242:243], v[206:207]
	v_pk_mul_f32 v[240:241], v[240:241], s[18:19] op_sel_hi:[1,0]
	v_pk_mul_f32 v[242:243], v[242:243], s[18:19] op_sel_hi:[1,0]
	v_pk_fma_f32 v[32:33], v[32:33], 0.5, v[240:241] op_sel_hi:[1,0,1]
	v_pk_fma_f32 v[34:35], v[34:35], 0.5, v[242:243] op_sel_hi:[1,0,1]
	global_store_dwordx4 v133, v[32:35], s[88:89] offset:576
	v_pk_mul_f32 v[162:163], v[162:163], s[16:17] op_sel_hi:[1,0]
	v_add_u32_e32 v133, 0x140000, v128
	v_fma_f32 v166, -v162, v162, v163
	v_max_f32_e32 v166, 0, v166
	v_add_f32_e32 v166, 0x3727c5ac, v166
	v_rsq_f32_e32 v166, v166
	s_nop 0
	s_waitcnt vmcnt(19)
	v_lshlrev_b32_e32 v134, 16, v224
	v_and_b32_e32 v135, 0xffff0000, v224
	v_lshlrev_b32_e32 v136, 16, v225
	v_and_b32_e32 v137, 0xffff0000, v225
	v_pk_add_f32 v[134:135], v[134:135], v[162:163] op_sel_hi:[1,0] neg_lo:[0,1] neg_hi:[0,1]
	v_pk_add_f32 v[136:137], v[136:137], v[162:163] op_sel_hi:[1,0] neg_lo:[0,1] neg_hi:[0,1]
	v_pk_mul_f32 v[134:135], v[134:135], v[166:167] op_sel_hi:[1,0]
	v_pk_mul_f32 v[136:137], v[136:137], v[166:167] op_sel_hi:[1,0]
	v_pk_fma_f32 v[134:135], v[176:177], v[134:135], v[192:193]
	v_pk_fma_f32 v[136:137], v[178:179], v[136:137], v[194:195]
	v_pk_mul_f32 v[134:135], v[134:135], s[18:19] op_sel_hi:[1,0]
	v_pk_mul_f32 v[136:137], v[136:137], s[18:19] op_sel_hi:[1,0]
	v_pk_fma_f32 v[28:29], v[28:29], 0.5, v[134:135] op_sel_hi:[1,0,1]
	v_pk_fma_f32 v[30:31], v[30:31], 0.5, v[136:137] op_sel_hi:[1,0,1]
	global_store_dwordx4 v133, v[28:31], s[88:89]
	s_waitcnt vmcnt(19)
; __device__ __forceinline__ float bf_lo(u32 v) { return __uint_as_float(v << 16); }
; __device__ __forceinline__ float bf_hi(u32 v) { return __uint_as_float(v & 0xFFFF0000u); }
; template <int EPI>
; __device__ __forceinline__ void gemm_phase(const u16* __restrict__ A, const u16* __restrict__ Bt, const int K,
;                                            const int nN, char* shm, const EpiArgs& ea) {
;     ...
;               float mu = 0.f, rstd = 1.f;
;               if (EPI != EPI_FFN1) row_stats(ea.st_in, row, mu, rstd);
;               float rs = 0.f, rq = 0.f;
; #pragma unroll
;               for (int bj = 0; bj < 2; ++bj) {
;                 uint2 pk[2];
; #pragma unroll
;                 for (int n = 0; n < 2; ++n) {
;                   const int col = cb + bj * 128 + n * 16;
;                   f32x4 c = acc[ai][bj][m][n];
;                   float h[4];
;                   if (EPI == EPI_FFN1) {
;                     float4 rv = *(const float4*)(ea.res + (size_t)row * DM + col);
;                     h[0] = rv.x; h[1] = rv.y; h[2] = rv.z; h[3] = rv.w;
;                   } else {
;                     uint2 yv = *(const uint2*)((const char*)ea.yb + tl_off(row, col, DM >> 6));
;                     float4 gv = *(const float4*)(ea.lng + col);
;                     float4 bv = *(const float4*)(ea.lnb + col);
;                     h[0] = (bf_lo(yv.x) - mu) * rstd * gv.x + bv.x; h[1] = (bf_hi(yv.x) - mu) * rstd * gv.y + bv.y;
;                     h[2] = (bf_lo(yv.y) - mu) * rstd * gv.z + bv.z; h[3] = (bf_hi(yv.y) - mu) * rstd * gv.w + bv.w;
;                   }
;                   float y[4];
;                   if (EPI == EPI_OUT) {
;                     float4 bo = *(const float4*)(ea.bias + col);
;                     y[0] = ALPHA * h[0] + c[0] + bo.x; y[1] = ALPHA * h[1] + c[1] + bo.y;
;                     y[2] = ALPHA * h[2] + c[2] + bo.z; y[3] = ALPHA * h[3] + c[3] + bo.w;
;                   } else {
; #pragma unroll
;                     for (int j = 0; j < 4; ++j) y[j] = ALPHA * h[j] + 0.5f * c[j];
;                   }
;                   if (EPI == EPI_FFN2) {
;                     *(float4*)(ea.outf + (size_t)row * DM + col) = make_float4(y[0], y[1], y[2], y[3]);
;     ...
;     brow = brow2; bcol = bcol2; pn = pn2;
	v_lshlrev_b32_e32 v240, 16, v226
	v_and_b32_e32 v241, 0xffff0000, v226
	v_lshlrev_b32_e32 v242, 16, v227
	v_and_b32_e32 v243, 0xffff0000, v227
	v_pk_add_f32 v[240:241], v[240:241], v[162:163] op_sel_hi:[1,0] neg_lo:[0,1] neg_hi:[0,1]
	v_pk_add_f32 v[242:243], v[242:243], v[162:163] op_sel_hi:[1,0] neg_lo:[0,1] neg_hi:[0,1]
	v_pk_mul_f32 v[240:241], v[240:241], v[166:167] op_sel_hi:[1,0]
	v_pk_mul_f32 v[242:243], v[242:243], v[166:167] op_sel_hi:[1,0]
	v_pk_fma_f32 v[240:241], v[180:181], v[240:241], v[196:197]
	v_pk_fma_f32 v[242:243], v[182:183], v[242:243], v[198:199]
	v_pk_mul_f32 v[240:241], v[240:241], s[18:19] op_sel_hi:[1,0]
	v_pk_mul_f32 v[242:243], v[242:243], s[18:19] op_sel_hi:[1,0]
	v_pk_fma_f32 v[24:25], v[24:25], 0.5, v[240:241] op_sel_hi:[1,0,1]
	v_pk_fma_f32 v[26:27], v[26:27], 0.5, v[242:243] op_sel_hi:[1,0,1]
	global_store_dwordx4 v133, v[24:27], s[88:89] offset:64
	s_waitcnt vmcnt(19)
	v_lshlrev_b32_e32 v134, 16, v228
	v_and_b32_e32 v135, 0xffff0000, v228
	v_lshlrev_b32_e32 v136, 16, v229
	v_and_b32_e32 v137, 0xffff0000, v229
	v_pk_add_f32 v[134:135], v[134:135], v[162:163] op_sel_hi:[1,0] neg_lo:[0,1] neg_hi:[0,1]
	v_pk_add_f32 v[136:137], v[136:137], v[162:163] op_sel_hi:[1,0] neg_lo:[0,1] neg_hi:[0,1]
	v_pk_mul_f32 v[134:135], v[134:135], v[166:167] op_sel_hi:[1,0]
	v_pk_mul_f32 v[136:137], v[136:137], v[166:167] op_sel_hi:[1,0]
	v_pk_fma_f32 v[134:135], v[184:185], v[134:135], v[200:201]
	v_pk_fma_f32 v[136:137], v[186:187], v[136:137], v[202:203]
	v_pk_mul_f32 v[134:135], v[134:135], s[18:19] op_sel_hi:[1,0]
	v_pk_mul_f32 v[136:137], v[136:137], s[18:19] op_sel_hi:[1,0]
	v_pk_fma_f32 v[20:21], v[20:21], 0.5, v[134:135] op_sel_hi:[1,0,1]
	v_pk_fma_f32 v[22:23], v[22:23], 0.5, v[136:137] op_sel_hi:[1,0,1]
	global_store_dwordx4 v133, v[20:23], s[88:89] offset:512
	s_waitcnt vmcnt(19)
	v_lshlrev_b32_e32 v240, 16, v230
	v_and_b32_e32 v241, 0xffff0000, v230
	v_lshlrev_b32_e32 v242, 16, v231
	v_and_b32_e32 v243, 0xffff0000, v231
	v_pk_add_f32 v[240:241], v[240:241], v[162:163] op_sel_hi:[1,0] neg_lo:[0,1] neg_hi:[0,1]
	v_pk_add_f32 v[242:243], v[242:243], v[162:163] op_sel_hi:[1,0] neg_lo:[0,1] neg_hi:[0,1]
	v_pk_mul_f32 v[240:241], v[240:241], v[166:167] op_sel_hi:[1,0]
	v_pk_mul_f32 v[242:243], v[242:243], v[166:167] op_sel_hi:[1,0]
	v_pk_fma_f32 v[240:241], v[188:189], v[240:241], v[204:205]
	v_pk_fma_f32 v[242:243], v[190:191], v[242:243], v[206:207]
	v_pk_mul_f32 v[240:241], v[240:241], s[18:19] op_sel_hi:[1,0]
	v_pk_mul_f32 v[242:243], v[242:243], s[18:19] op_sel_hi:[1,0]
	v_pk_fma_f32 v[16:17], v[16:17], 0.5, v[240:241] op_sel_hi:[1,0,1]
	v_pk_fma_f32 v[18:19], v[18:19], 0.5, v[242:243] op_sel_hi:[1,0,1]
	global_store_dwordx4 v133, v[16:19], s[88:89] offset:576
	v_pk_mul_f32 v[164:165], v[164:165], s[16:17] op_sel_hi:[1,0]
	v_add_u32_e32 v133, 0x160000, v128
	v_fma_f32 v168, -v164, v164, v165
	v_max_f32_e32 v168, 0, v168
	v_add_f32_e32 v168, 0x3727c5ac, v168
	v_rsq_f32_e32 v168, v168
	s_nop 0
	s_waitcnt vmcnt(15)
	v_lshlrev_b32_e32 v134, 16, v232
	v_and_b32_e32 v135, 0xffff0000, v232
	v_lshlrev_b32_e32 v136, 16, v233
	v_and_b32_e32 v137, 0xffff0000, v233
	v_pk_add_f32 v[134:135], v[134:135], v[164:165] op_sel_hi:[1,0] neg_lo:[0,1] neg_hi:[0,1]
	v_pk_add_f32 v[136:137], v[136:137], v[164:165] op_sel_hi:[1,0] neg_lo:[0,1] neg_hi:[0,1]
	v_pk_mul_f32 v[134:135], v[134:135], v[168:169] op_sel_hi:[1,0]
	v_pk_mul_f32 v[136:137], v[136:137], v[168:169] op_sel_hi:[1,0]
	v_pk_fma_f32 v[134:135], v[176:177], v[134:135], v[192:193]
	v_pk_fma_f32 v[136:137], v[178:179], v[136:137], v[194:195]
	v_pk_mul_f32 v[134:135], v[134:135], s[18:19] op_sel_hi:[1,0]
	v_pk_mul_f32 v[136:137], v[136:137], s[18:19] op_sel_hi:[1,0]
	v_pk_fma_f32 v[12:13], v[12:13], 0.5, v[134:135] op_sel_hi:[1,0,1]
	v_pk_fma_f32 v[14:15], v[14:15], 0.5, v[136:137] op_sel_hi:[1,0,1]
	global_store_dwordx4 v133, v[12:15], s[88:89]
	s_waitcnt vmcnt(15)
	v_lshlrev_b32_e32 v240, 16, v234
	v_and_b32_e32 v241, 0xffff0000, v234
	v_lshlrev_b32_e32 v242, 16, v235
	v_and_b32_e32 v243, 0xffff0000, v235
	v_pk_add_f32 v[240:241], v[240:241], v[164:165] op_sel_hi:[1,0] neg_lo:[0,1] neg_hi:[0,1]
	v_pk_add_f32 v[242:243], v[242:243], v[164:165] op_sel_hi:[1,0] neg_lo:[0,1] neg_hi:[0,1]
	v_pk_mul_f32 v[240:241], v[240:241], v[168:169] op_sel_hi:[1,0]
	v_pk_mul_f32 v[242:243], v[242:243], v[168:169] op_sel_hi:[1,0]
	v_pk_fma_f32 v[240:241], v[180:181], v[240:241], v[196:197]
	v_pk_fma_f32 v[242:243], v[182:183], v[242:243], v[198:199]
	v_pk_mul_f32 v[240:241], v[240:241], s[18:19] op_sel_hi:[1,0]
	v_pk_mul_f32 v[242:243], v[242:243], s[18:19] op_sel_hi:[1,0]
	v_pk_fma_f32 v[8:9], v[8:9], 0.5, v[240:241] op_sel_hi:[1,0,1]
	v_pk_fma_f32 v[10:11], v[10:11], 0.5, v[242:243] op_sel_hi:[1,0,1]
	global_store_dwordx4 v133, v[8:11], s[88:89] offset:64
	s_waitcnt vmcnt(15)
	v_lshlrev_b32_e32 v134, 16, v236
	v_and_b32_e32 v135, 0xffff0000, v236
	v_lshlrev_b32_e32 v136, 16, v237
	v_and_b32_e32 v137, 0xffff0000, v237
	v_pk_add_f32 v[134:135], v[134:135], v[164:165] op_sel_hi:[1,0] neg_lo:[0,1] neg_hi:[0,1]
	v_pk_add_f32 v[136:137], v[136:137], v[164:165] op_sel_hi:[1,0] neg_lo:[0,1] neg_hi:[0,1]
	v_pk_mul_f32 v[134:135], v[134:135], v[168:169] op_sel_hi:[1,0]
	v_pk_mul_f32 v[136:137], v[136:137], v[168:169] op_sel_hi:[1,0]
	v_pk_fma_f32 v[134:135], v[184:185], v[134:135], v[200:201]
	v_pk_fma_f32 v[136:137], v[186:187], v[136:137], v[202:203]
	v_pk_mul_f32 v[134:135], v[134:135], s[18:19] op_sel_hi:[1,0]
	v_pk_mul_f32 v[136:137], v[136:137], s[18:19] op_sel_hi:[1,0]
	v_pk_fma_f32 v[4:5], v[4:5], 0.5, v[134:135] op_sel_hi:[1,0,1]
	v_pk_fma_f32 v[6:7], v[6:7], 0.5, v[136:137] op_sel_hi:[1,0,1]
	global_store_dwordx4 v133, v[4:7], s[88:89] offset:512
	s_waitcnt vmcnt(15)
	v_lshlrev_b32_e32 v240, 16, v238
	v_and_b32_e32 v241, 0xffff0000, v238
	v_lshlrev_b32_e32 v242, 16, v239
	v_and_b32_e32 v243, 0xffff0000, v239
	v_pk_add_f32 v[240:241], v[240:241], v[164:165] op_sel_hi:[1,0] neg_lo:[0,1] neg_hi:[0,1]
	v_pk_add_f32 v[242:243], v[242:243], v[164:165] op_sel_hi:[1,0] neg_lo:[0,1] neg_hi:[0,1]
	v_pk_mul_f32 v[240:241], v[240:241], v[168:169] op_sel_hi:[1,0]
	v_pk_mul_f32 v[242:243], v[242:243], v[168:169] op_sel_hi:[1,0]
	v_pk_fma_f32 v[240:241], v[188:189], v[240:241], v[204:205]
	v_pk_fma_f32 v[242:243], v[190:191], v[242:243], v[206:207]
	v_pk_mul_f32 v[240:241], v[240:241], s[18:19] op_sel_hi:[1,0]
	v_pk_mul_f32 v[242:243], v[242:243], s[18:19] op_sel_hi:[1,0]
	v_pk_fma_f32 v[0:1], v[0:1], 0.5, v[240:241] op_sel_hi:[1,0,1]
	v_pk_fma_f32 v[2:3], v[2:3], 0.5, v[242:243] op_sel_hi:[1,0,1]
	global_store_dwordx4 v133, v[0:3], s[88:89] offset:576
	s_mov_b32 s33, s46
	s_mov_b32 s47, s45
	s_andn2_b64 vcc, exec, s[20:21]
	s_cbranch_vccz .LBB0_636
	s_branch .LBB0_626

; __device__ __forceinline__ unsigned xb_add(unsigned* p, unsigned v) { return __hip_atomic_fetch_add(p, v, __ATOMIC_RELAXED, __HIP_MEMORY_SCOPE_AGENT); }
; #define PHASE(i) if (p.ph_lo <= (i) && (i) < p.ph_hi && ((first ? (void)0 : xcd_barrier(xb)), first = false, true))
; __device__ __forceinline__ void xcd_barrier(const XcdBarrier& b) {
;     asm volatile("s_waitcnt vmcnt(0)" ::: "memory");
;     __syncthreads();
;     if (threadIdx.x == 0) {
;         unsigned* bar = b.bar;
;         __builtin_amdgcn_s_waitcnt(0);
;         const unsigned old = xb_add(&bar[XB_XSUB(b.x)], 1u);
;         const unsigned gen = old / b.nloc;
;         if (old + 1u == (gen + 1u) * b.nloc) {
; __global__ __launch_bounds__(512, 2) void mega(Params p) {
;     ...
;   PHASE(8) ln_phase(p.out, p.ln_c_g, p.ln_c_b, nullptr);
.LBB0_637:
	s_cmp_eq_u32 s94, 0x100
	s_cbranch_scc1 .LBB0_680
	s_cmp_gt_i32 s92, 8
	s_cselect_b64 s[2:3], -1, 0
	s_cmp_lt_i32 s93, 9
	s_cselect_b64 s[4:5], -1, 0
	s_or_b64 s[2:3], s[2:3], s[4:5]
	s_and_b64 vcc, exec, s[2:3]
	s_cbranch_vccnz .LBB0_680
	s_xor_b64 s[0:1], s[0:1], -1
	s_andn2_b64 vcc, exec, s[0:1]
	s_cbranch_vccnz .LBB0_677
	s_waitcnt vmcnt(0)
	s_waitcnt vmcnt(0)
	s_barrier
	s_mov_b64 s[0:1], exec
	v_readlane_b32 s2, v244, 4
	v_readlane_b32 s3, v244, 5
	s_and_b64 s[2:3], s[0:1], s[2:3]
	s_mov_b64 exec, s[2:3]
	s_cbranch_execz .LBB0_676
	s_mov_b64 s[2:3], exec
	v_mbcnt_lo_u32_b32 v0, s2, 0
	v_readlane_b32 s4, v244, 6
	v_mbcnt_hi_u32_b32 v0, s3, v0
	s_lshl_b32 s20, s4, 6
	s_mov_b32 s7, 0
	v_cmp_eq_u32_e32 vcc, 0, v0
	s_waitcnt vmcnt(0) expcnt(0) lgkmcnt(0)
	s_and_saveexec_b64 s[4:5], vcc
	s_cbranch_execz .LBB0_642
	s_add_i32 s6, s20, 0x500
	s_lshl_b64 s[6:7], s[6:7], 2
	v_readlane_b32 s8, v244, 2
	v_readlane_b32 s9, v244, 3
	s_add_u32 s6, s8, s6
	s_addc_u32 s7, s9, s7
	s_bcnt1_i32_b64 s2, s[2:3]
	v_mov_b32_e32 v1, 0
	v_mov_b32_e32 v2, s2
	global_atomic_add v1, v1, v2, s[6:7] sc0
